# P0 filter f1/f2 contractions: all weight loads issued up front; MIX: second-half workgroups skip the fallback fetch on the sample-scan queue
# speedup vs baseline: 1.3024x; 1.0108x over previous
.LBB0_98:
	s_and_b64 vcc, exec, s[0:1]
	s_cbranch_vccz .LBB0_146
	s_ashr_i32 s71, s70, 31
	s_lshl_b64 s[0:1], s[70:71], 2
	v_readlane_b32 s2, v255, 15
	v_readlane_b32 s3, v255, 16
	s_add_u32 s36, s2, s0
	s_addc_u32 s37, s3, s1
	s_lshl_b32 s26, s70, 7
	s_mul_i32 s28, s70, 0x920000
	s_ashr_i32 s27, s26, 31
	v_readlane_b32 s2, v254, 37
	s_mul_hi_i32 s25, s70, 0x920000
	s_add_u32 s4, s2, s28
	v_readlane_b32 s2, v254, 38
	s_addc_u32 s5, s2, s25
	v_writelane_b32 v255, s4, 38
	v_readlane_b32 s2, v254, 45
	v_readlane_b32 s3, v254, 46
	v_writelane_b32 v255, s5, 39
	v_writelane_b32 v255, s16, 40
	v_writelane_b32 v255, s18, 42
	s_add_u32 s2, s2, s0
	s_addc_u32 s3, s3, s1
	v_writelane_b32 v255, s19, 43
	v_readlane_b32 s4, v252, 49
	s_lshl_b64 s[0:1], s[26:27], 2
	v_readlane_b32 s12, v252, 57
	v_readlane_b32 s13, v252, 58
	s_add_u32 s12, s12, s0
	s_addc_u32 s13, s13, s1
	s_add_u32 s0, s96, s28
	v_readlane_b32 s14, v252, 59
	v_readlane_b32 s18, v252, 63
	v_readlane_b32 s19, v253, 0
	s_addc_u32 s1, s97, s25
	v_readlane_b32 s15, v252, 60
	v_readlane_b32 s16, v252, 61
	v_readlane_b32 s18, v255, 42
	s_add_u32 s14, s0, 0x5f34000
	s_mov_b32 s0, s70
	v_readlane_b32 s8, v252, 53
	v_readlane_b32 s9, v252, 54
	v_readlane_b32 s10, v252, 55
	v_readlane_b32 s11, v252, 56
	v_readlane_b32 s19, v255, 43
	v_readlane_b32 s16, v255, 40
	s_addc_u32 s15, s1, 0
	v_writelane_b32 v255, s0, 44
	s_mov_b64 s[10:11], s[2:3]
	s_mov_b64 s[8:9], s[36:37]
	v_writelane_b32 v255, s1, 45
	v_readlane_b32 s5, v252, 50
	v_readlane_b32 s6, v252, 51
	v_readlane_b32 s7, v252, 52
	v_readlane_b32 s17, v252, 62
	v_readlane_b32 s101, v252, 0
	s_lshr_b32 s98, s101, 8
	s_and_b32 s98, s98, 1
	s_lshl_b32 s99, s98, 2
	s_or_b32 s99, s99, s98
	s_and_b32 s101, s101, 0xff
	s_lshr_b32 s100, s101, 5
	s_add_i32 s100, s100, 4
	s_lshl_b32 s100, s100, 6
	s_and_b32 s101, s101, 31
	s_add_i32 s100, s100, s101
	s_add_i32 s100, s100, 1
	s_lshl_b32 s100, s100, 2
	s_add_u32 s100, s100, 0x227a6200
	s_add_u32 s100, s96, s100
	s_addc_u32 s101, s97, 0
	s_cmp_eq_u32 s98, 0
	s_cbranch_scc0 .Lq_init_done
	s_or_b32 s99, s99, 2
	v_readlane_b32 s26, v253, 1
	v_readlane_b32 s27, v253, 2
	s_and_saveexec_b64 s[28:29], s[26:27]
	v_mov_b32_e32 v1, 1
	global_atomic_add v131, v1, s[100:101]
	s_or_b64 exec, exec, s[28:29]

.LBB0_456:
	v_lshl_add_u64 v[196:197], v[6:7], 0, s[26:27]
	global_load_dword v132, v[196:197], off
	global_load_dword v133, v[196:197], off offset:256
	global_load_dword v134, v[196:197], off offset:512
	global_load_dword v135, v[196:197], off offset:768
	global_load_dword v136, v[196:197], off offset:1024
	global_load_dword v137, v[196:197], off offset:1280
	global_load_dword v138, v[196:197], off offset:1536
	global_load_dword v139, v[196:197], off offset:1792
	global_load_dword v140, v[196:197], off offset:2048
	global_load_dword v141, v[196:197], off offset:2304
	global_load_dword v142, v[196:197], off offset:2560
	s_add_u32 s26, s26, 0xb00
	s_addc_u32 s27, s27, 0
	v_lshl_add_u64 v[196:197], v[6:7], 0, s[26:27]
	global_load_dword v143, v[196:197], off
	global_load_dword v144, v[196:197], off offset:256
	global_load_dword v145, v[196:197], off offset:512
	global_load_dword v146, v[196:197], off offset:768
	global_load_dword v147, v[196:197], off offset:1024
	global_load_dword v148, v[196:197], off offset:1280
	global_load_dword v149, v[196:197], off offset:1536
	global_load_dword v150, v[196:197], off offset:1792
	global_load_dword v151, v[196:197], off offset:2048
	global_load_dword v152, v[196:197], off offset:2304
	global_load_dword v153, v[196:197], off offset:2560
	s_add_u32 s26, s26, 0xb00
	s_addc_u32 s27, s27, 0
	v_lshl_add_u64 v[196:197], v[6:7], 0, s[26:27]
	global_load_dword v154, v[196:197], off
	global_load_dword v155, v[196:197], off offset:256
	global_load_dword v156, v[196:197], off offset:512
	global_load_dword v157, v[196:197], off offset:768
	global_load_dword v158, v[196:197], off offset:1024
	global_load_dword v159, v[196:197], off offset:1280
	global_load_dword v160, v[196:197], off offset:1536
	global_load_dword v161, v[196:197], off offset:1792
	global_load_dword v162, v[196:197], off offset:2048
	global_load_dword v163, v[196:197], off offset:2304
	global_load_dword v164, v[196:197], off offset:2560
	s_add_u32 s26, s26, 0xb00
	s_addc_u32 s27, s27, 0
	s_cmpk_eq_i32 s26, 0x2100
	ds_read2_b32 v[10:11], v4 offset1:1
	ds_read2_b32 v[12:13], v4 offset0:2 offset1:3
	ds_read2_b32 v[14:15], v4 offset0:4 offset1:5
	ds_read2_b32 v[16:17], v4 offset0:6 offset1:7
	ds_read2_b32 v[18:19], v4 offset0:8 offset1:9
	ds_read_b32 v29, v4 offset:40
	v_add_u32_e32 v4, 44, v4
	s_waitcnt vmcnt(32) lgkmcnt(5)
	v_fmac_f32_e32 v3, v10, v132
	s_waitcnt vmcnt(31)
	v_fmac_f32_e32 v3, v11, v133
	s_waitcnt vmcnt(30) lgkmcnt(4)
	v_fmac_f32_e32 v3, v12, v134
	s_waitcnt vmcnt(29)
	v_fmac_f32_e32 v3, v13, v135
	s_waitcnt vmcnt(28) lgkmcnt(3)
	v_fmac_f32_e32 v3, v14, v136
	s_waitcnt vmcnt(27)
	v_fmac_f32_e32 v3, v15, v137
	s_waitcnt vmcnt(26) lgkmcnt(2)
	v_fmac_f32_e32 v3, v16, v138
	s_waitcnt vmcnt(25)
	v_fmac_f32_e32 v3, v17, v139
	s_waitcnt vmcnt(24) lgkmcnt(1)
	v_fmac_f32_e32 v3, v18, v140
	s_waitcnt vmcnt(23)
	v_fmac_f32_e32 v3, v19, v141
	s_waitcnt vmcnt(22) lgkmcnt(0)
	v_fmac_f32_e32 v3, v29, v142
	ds_read2_b32 v[10:11], v4 offset1:1
	ds_read2_b32 v[12:13], v4 offset0:2 offset1:3
	ds_read2_b32 v[14:15], v4 offset0:4 offset1:5
	ds_read2_b32 v[16:17], v4 offset0:6 offset1:7
	ds_read2_b32 v[18:19], v4 offset0:8 offset1:9
	ds_read_b32 v29, v4 offset:40
	v_add_u32_e32 v4, 44, v4
	s_waitcnt vmcnt(21) lgkmcnt(5)
	v_fmac_f32_e32 v3, v10, v143
	s_waitcnt vmcnt(20)
	v_fmac_f32_e32 v3, v11, v144
	s_waitcnt vmcnt(19) lgkmcnt(4)
	v_fmac_f32_e32 v3, v12, v145
	s_waitcnt vmcnt(18)
	v_fmac_f32_e32 v3, v13, v146
	s_waitcnt vmcnt(17) lgkmcnt(3)
	v_fmac_f32_e32 v3, v14, v147
	s_waitcnt vmcnt(16)
	v_fmac_f32_e32 v3, v15, v148
	s_waitcnt vmcnt(15) lgkmcnt(2)
	v_fmac_f32_e32 v3, v16, v149
	s_waitcnt vmcnt(14)
	v_fmac_f32_e32 v3, v17, v150
	s_waitcnt vmcnt(13) lgkmcnt(1)
	v_fmac_f32_e32 v3, v18, v151
	s_waitcnt vmcnt(12)
	v_fmac_f32_e32 v3, v19, v152
	s_waitcnt vmcnt(11) lgkmcnt(0)
	v_fmac_f32_e32 v3, v29, v153
	ds_read2_b32 v[10:11], v4 offset1:1
	ds_read2_b32 v[12:13], v4 offset0:2 offset1:3
	ds_read2_b32 v[14:15], v4 offset0:4 offset1:5
	ds_read2_b32 v[16:17], v4 offset0:6 offset1:7
	ds_read2_b32 v[18:19], v4 offset0:8 offset1:9
	ds_read_b32 v29, v4 offset:40
	v_add_u32_e32 v4, 44, v4
	s_waitcnt vmcnt(10) lgkmcnt(5)
	v_fmac_f32_e32 v3, v10, v154
	s_waitcnt vmcnt(9)
	v_fmac_f32_e32 v3, v11, v155
	s_waitcnt vmcnt(8) lgkmcnt(4)
	v_fmac_f32_e32 v3, v12, v156
	s_waitcnt vmcnt(7)
	v_fmac_f32_e32 v3, v13, v157
	s_waitcnt vmcnt(6) lgkmcnt(3)
	v_fmac_f32_e32 v3, v14, v158
	s_waitcnt vmcnt(5)
	v_fmac_f32_e32 v3, v15, v159
	s_waitcnt vmcnt(4) lgkmcnt(2)
	v_fmac_f32_e32 v3, v16, v160
	s_waitcnt vmcnt(3)
	v_fmac_f32_e32 v3, v17, v161
	s_waitcnt vmcnt(2) lgkmcnt(1)
	v_fmac_f32_e32 v3, v18, v162
	s_waitcnt vmcnt(1)
	v_fmac_f32_e32 v3, v19, v163
	s_waitcnt vmcnt(0) lgkmcnt(0)
	v_fmac_f32_e32 v3, v29, v164
	v_readlane_b32 s52, v252, 1
	s_lshl_b32 s44, s28, 2
	v_readlane_b32 s66, v252, 15
	v_readlane_b32 s67, v252, 16
	s_add_u32 s26, s66, s44
	s_addc_u32 s27, s67, 0
	v_lshlrev_b32_e32 v2, 2, v2
	global_load_dword v10, v2, s[26:27]
	s_brev_b32 s4, 18
	v_readlane_b32 s53, v252, 2
	v_readlane_b32 s54, v252, 3
	v_readlane_b32 s55, v252, 4
	v_readlane_b32 s56, v252, 5
	v_readlane_b32 s57, v252, 6
	v_readlane_b32 s58, v252, 7
	v_readlane_b32 s59, v252, 8
	v_readlane_b32 s60, v252, 9
	v_readlane_b32 s61, v252, 10
	v_readlane_b32 s62, v252, 11
	v_readlane_b32 s63, v252, 12
	v_readlane_b32 s64, v252, 13
	v_readlane_b32 s65, v252, 14
	s_waitcnt vmcnt(0)
	v_mul_f32_e32 v8, v3, v10
	v_and_b32_e32 v11, 0x7fffffff, v8
	v_cmp_nlt_f32_e64 s[28:29], |v8|, s4
	s_and_saveexec_b64 s[36:37], s[28:29]
	s_xor_b64 s[28:29], exec, s[36:37]
	s_cbranch_execz .LBB0_459
	v_lshrrev_b32_e32 v3, 23, v11
	v_add_u32_e32 v3, 0xffffff88, v3
	v_cmp_lt_u32_e32 vcc, 63, v3
	s_mov_b32 s4, 0xfe5163ab
	v_mov_b32_e32 v13, v131
	v_cndmask_b32_e32 v4, 0, v215, vcc
	v_add_u32_e32 v3, v4, v3
	v_cmp_lt_u32_e64 s[36:37], 31, v3
	v_mov_b32_e32 v15, v131
	v_mov_b32_e32 v17, v131
	v_cndmask_b32_e64 v4, 0, v216, s[36:37]
	v_add_u32_e32 v3, v4, v3
	v_cmp_lt_u32_e64 s[38:39], 31, v3
	v_mov_b32_e32 v19, v131
	v_mov_b32_e32 v21, v131
	v_cndmask_b32_e64 v4, 0, v216, s[38:39]
	v_add_u32_e32 v3, v4, v3
	v_and_b32_e32 v4, 0x7fffff, v11
	v_or_b32_e32 v24, 0x800000, v4
	v_mad_u64_u32 v[4:5], s[40:41], v24, s4, 0
	v_mov_b32_e32 v12, v5
	s_mov_b32 s4, 0x3c439041
	v_mad_u64_u32 v[12:13], s[40:41], v24, s4, v[12:13]
	v_mov_b32_e32 v14, v13
	s_mov_b32 s4, 0xdb629599
	v_mad_u64_u32 v[14:15], s[40:41], v24, s4, v[14:15]
	v_mov_b32_e32 v16, v15
	s_mov_b32 s4, 0xf534ddc0
	v_mad_u64_u32 v[16:17], s[40:41], v24, s4, v[16:17]
	v_mov_b32_e32 v18, v17
	s_mov_b32 s4, 0xfc2757d1
	v_mad_u64_u32 v[18:19], s[40:41], v24, s4, v[18:19]
	v_mov_b32_e32 v20, v19
	s_mov_b32 s4, 0x4e441529
	v_mad_u64_u32 v[20:21], s[40:41], v24, s4, v[20:21]
	v_mov_b32_e32 v22, v21
	v_mov_b32_e32 v23, v131
	s_mov_b32 s4, 0xa2f9836e
	v_mad_u64_u32 v[22:23], s[40:41], v24, s4, v[22:23]
	v_cndmask_b32_e32 v5, v20, v16, vcc
	v_cndmask_b32_e32 v13, v22, v18, vcc
	v_cndmask_b32_e32 v17, v23, v20, vcc
	v_cndmask_b32_e64 v15, v13, v5, s[36:37]
	v_cndmask_b32_e64 v13, v17, v13, s[36:37]
	v_cndmask_b32_e32 v17, v18, v14, vcc
	v_cndmask_b32_e64 v5, v5, v17, s[36:37]
	v_cndmask_b32_e64 v13, v13, v15, s[38:39]
	v_cndmask_b32_e64 v15, v15, v5, s[38:39]
	v_sub_u32_e32 v18, 32, v3
	v_alignbit_b32 v19, v13, v15, v18
	v_cmp_eq_u32_e64 s[40:41], 0, v3
	v_cndmask_b32_e32 v12, v16, v12, vcc
	v_cndmask_b32_e32 v4, v14, v4, vcc
	v_cndmask_b32_e64 v3, v19, v13, s[40:41]
	v_cndmask_b32_e64 v13, v17, v12, s[36:37]
	v_cndmask_b32_e64 v5, v5, v13, s[38:39]
	v_alignbit_b32 v16, v15, v5, v18
	v_cndmask_b32_e64 v15, v16, v15, s[40:41]
	v_bfe_u32 v19, v3, 29, 1
	v_cndmask_b32_e64 v4, v12, v4, s[36:37]
	v_alignbit_b32 v16, v3, v15, 30
	v_sub_u32_e32 v20, 0, v19
	v_cndmask_b32_e64 v4, v13, v4, s[38:39]
	v_xor_b32_e32 v16, v16, v20
	v_alignbit_b32 v12, v5, v4, v18
	v_cndmask_b32_e64 v5, v12, v5, s[40:41]
	v_ffbh_u32_e32 v13, v16
	v_alignbit_b32 v12, v15, v5, 30
	v_min_u32_e32 v13, 32, v13
	v_alignbit_b32 v4, v5, v4, 30
	v_xor_b32_e32 v12, v12, v20
	v_sub_u32_e32 v14, 31, v13
	v_xor_b32_e32 v4, v4, v20
	v_alignbit_b32 v15, v16, v12, v14
	v_alignbit_b32 v4, v12, v4, v14
	v_alignbit_b32 v5, v15, v4, 9
	v_ffbh_u32_e32 v12, v5
	v_min_u32_e32 v12, 32, v12
	v_lshrrev_b32_e32 v17, 29, v3
	v_not_b32_e32 v14, v12
	v_alignbit_b32 v4, v5, v4, v14
	v_lshlrev_b32_e32 v5, 31, v17
	v_or_b32_e32 v14, 0x33000000, v5
	v_add_lshl_u32 v12, v12, v13, 23
	v_lshrrev_b32_e32 v4, 9, v4
	v_sub_u32_e32 v12, v14, v12
	v_or_b32_e32 v5, 0.5, v5
	v_lshlrev_b32_e32 v13, 23, v13
	v_or_b32_e32 v4, v12, v4
	v_lshrrev_b32_e32 v12, 9, v15
	v_sub_u32_e32 v5, v5, v13
	v_or_b32_e32 v5, v12, v5
	v_mul_f32_e32 v12, 0x3fc90fda, v5
	s_mov_b32 s4, 0x3fc90fda
	v_fma_f32 v13, v5, s4, -v12
	v_fmac_f32_e32 v13, 0x33a22168, v5
	v_fmac_f32_e32 v13, 0x3fc90fda, v4
	v_lshrrev_b32_e32 v3, 30, v3
	v_add_f32_e32 v13, v12, v13
	v_add_u32_e32 v12, v19, v3

.LBB0_462:
	v_lshl_add_u64 v[196:197], v[6:7], 0, s[26:27]
	global_load_dword v132, v[196:197], off
	global_load_dword v133, v[196:197], off offset:256
	global_load_dword v134, v[196:197], off offset:512
	global_load_dword v135, v[196:197], off offset:768
	global_load_dword v136, v[196:197], off offset:1024
	global_load_dword v137, v[196:197], off offset:1280
	global_load_dword v138, v[196:197], off offset:1536
	global_load_dword v139, v[196:197], off offset:1792
	global_load_dword v140, v[196:197], off offset:2048
	global_load_dword v141, v[196:197], off offset:2304
	global_load_dword v142, v[196:197], off offset:2560
	s_add_u32 s26, s26, 0xb00
	s_addc_u32 s27, s27, 0
	v_lshl_add_u64 v[196:197], v[6:7], 0, s[26:27]
	global_load_dword v143, v[196:197], off
	global_load_dword v144, v[196:197], off offset:256
	global_load_dword v145, v[196:197], off offset:512
	global_load_dword v146, v[196:197], off offset:768
	global_load_dword v147, v[196:197], off offset:1024
	global_load_dword v148, v[196:197], off offset:1280
	global_load_dword v149, v[196:197], off offset:1536
	global_load_dword v150, v[196:197], off offset:1792
	global_load_dword v151, v[196:197], off offset:2048
	global_load_dword v152, v[196:197], off offset:2304
	global_load_dword v153, v[196:197], off offset:2560
	s_add_u32 s26, s26, 0xb00
	s_addc_u32 s27, s27, 0
	v_lshl_add_u64 v[196:197], v[6:7], 0, s[26:27]
	global_load_dword v154, v[196:197], off
	global_load_dword v155, v[196:197], off offset:256
	global_load_dword v156, v[196:197], off offset:512
	global_load_dword v157, v[196:197], off offset:768
	global_load_dword v158, v[196:197], off offset:1024
	global_load_dword v159, v[196:197], off offset:1280
	global_load_dword v160, v[196:197], off offset:1536
	global_load_dword v161, v[196:197], off offset:1792
	global_load_dword v162, v[196:197], off offset:2048
	global_load_dword v163, v[196:197], off offset:2304
	global_load_dword v164, v[196:197], off offset:2560
	s_add_u32 s26, s26, 0xb00
	s_addc_u32 s27, s27, 0
	s_cmpk_lg_i32 s26, 0x2100
	ds_read2_b32 v[12:13], v3 offset1:1
	ds_read2_b32 v[14:15], v3 offset0:2 offset1:3
	ds_read2_b32 v[16:17], v3 offset0:4 offset1:5
	ds_read2_b32 v[18:19], v3 offset0:6 offset1:7
	ds_read2_b32 v[20:21], v3 offset0:8 offset1:9
	ds_read_b32 v32, v3 offset:40
	v_add_u32_e32 v3, 44, v3
	s_waitcnt vmcnt(32) lgkmcnt(5)
	v_fmac_f32_e32 v9, v12, v132
	s_waitcnt vmcnt(31)
	v_fmac_f32_e32 v9, v13, v133
	s_waitcnt vmcnt(30) lgkmcnt(4)
	v_fmac_f32_e32 v9, v14, v134
	s_waitcnt vmcnt(29)
	v_fmac_f32_e32 v9, v15, v135
	s_waitcnt vmcnt(28) lgkmcnt(3)
	v_fmac_f32_e32 v9, v16, v136
	s_waitcnt vmcnt(27)
	v_fmac_f32_e32 v9, v17, v137
	s_waitcnt vmcnt(26) lgkmcnt(2)
	v_fmac_f32_e32 v9, v18, v138
	s_waitcnt vmcnt(25)
	v_fmac_f32_e32 v9, v19, v139
	s_waitcnt vmcnt(24) lgkmcnt(1)
	v_fmac_f32_e32 v9, v20, v140
	s_waitcnt vmcnt(23)
	v_fmac_f32_e32 v9, v21, v141
	s_waitcnt vmcnt(22) lgkmcnt(0)
	v_fmac_f32_e32 v9, v32, v142
	ds_read2_b32 v[12:13], v3 offset1:1
	ds_read2_b32 v[14:15], v3 offset0:2 offset1:3
	ds_read2_b32 v[16:17], v3 offset0:4 offset1:5
	ds_read2_b32 v[18:19], v3 offset0:6 offset1:7
	ds_read2_b32 v[20:21], v3 offset0:8 offset1:9
	ds_read_b32 v32, v3 offset:40
	v_add_u32_e32 v3, 44, v3
	s_waitcnt vmcnt(21) lgkmcnt(5)
	v_fmac_f32_e32 v9, v12, v143
	s_waitcnt vmcnt(20)
	v_fmac_f32_e32 v9, v13, v144
	s_waitcnt vmcnt(19) lgkmcnt(4)
	v_fmac_f32_e32 v9, v14, v145
	s_waitcnt vmcnt(18)
	v_fmac_f32_e32 v9, v15, v146
	s_waitcnt vmcnt(17) lgkmcnt(3)
	v_fmac_f32_e32 v9, v16, v147
	s_waitcnt vmcnt(16)
	v_fmac_f32_e32 v9, v17, v148
	s_waitcnt vmcnt(15) lgkmcnt(2)
	v_fmac_f32_e32 v9, v18, v149
	s_waitcnt vmcnt(14)
	v_fmac_f32_e32 v9, v19, v150
	s_waitcnt vmcnt(13) lgkmcnt(1)
	v_fmac_f32_e32 v9, v20, v151
	s_waitcnt vmcnt(12)
	v_fmac_f32_e32 v9, v21, v152
	s_waitcnt vmcnt(11) lgkmcnt(0)
	v_fmac_f32_e32 v9, v32, v153
	ds_read2_b32 v[12:13], v3 offset1:1
	ds_read2_b32 v[14:15], v3 offset0:2 offset1:3
	ds_read2_b32 v[16:17], v3 offset0:4 offset1:5
	ds_read2_b32 v[18:19], v3 offset0:6 offset1:7
	ds_read2_b32 v[20:21], v3 offset0:8 offset1:9
	ds_read_b32 v32, v3 offset:40
	v_add_u32_e32 v3, 44, v3
	s_waitcnt vmcnt(10) lgkmcnt(5)
	v_fmac_f32_e32 v9, v12, v154
	s_waitcnt vmcnt(9)
	v_fmac_f32_e32 v9, v13, v155
	s_waitcnt vmcnt(8) lgkmcnt(4)
	v_fmac_f32_e32 v9, v14, v156
	s_waitcnt vmcnt(7)
	v_fmac_f32_e32 v9, v15, v157
	s_waitcnt vmcnt(6) lgkmcnt(3)
	v_fmac_f32_e32 v9, v16, v158
	s_waitcnt vmcnt(5)
	v_fmac_f32_e32 v9, v17, v159
	s_waitcnt vmcnt(4) lgkmcnt(2)
	v_fmac_f32_e32 v9, v18, v160
	s_waitcnt vmcnt(3)
	v_fmac_f32_e32 v9, v19, v161
	s_waitcnt vmcnt(2) lgkmcnt(1)
	v_fmac_f32_e32 v9, v20, v162
	s_waitcnt vmcnt(1)
	v_fmac_f32_e32 v9, v21, v163
	s_waitcnt vmcnt(0) lgkmcnt(0)
	v_fmac_f32_e32 v9, v32, v164
	v_mul_f32_e32 v3, v10, v9
	s_brev_b32 s4, 18
	v_and_b32_e32 v6, 0x7fffffff, v3
	v_cmp_nlt_f32_e64 s[26:27], |v3|, s4
	s_and_saveexec_b64 s[28:29], s[26:27]
	s_xor_b64 s[26:27], exec, s[28:29]
	s_cbranch_execz .LBB0_465
	v_lshrrev_b32_e32 v7, 23, v6
	v_add_u32_e32 v7, 0xffffff88, v7
	v_cmp_lt_u32_e32 vcc, 63, v7
	s_mov_b32 s4, 0xfe5163ab
	v_mov_b32_e32 v13, v131
	v_cndmask_b32_e32 v9, 0, v215, vcc
	v_add_u32_e32 v7, v9, v7
	v_cmp_lt_u32_e64 s[36:37], 31, v7
	v_mov_b32_e32 v15, v131
	v_mov_b32_e32 v17, v131
	v_cndmask_b32_e64 v9, 0, v216, s[36:37]
	v_add_u32_e32 v7, v9, v7
	v_cmp_lt_u32_e64 s[38:39], 31, v7
	v_mov_b32_e32 v19, v131
	v_mov_b32_e32 v21, v131
	v_cndmask_b32_e64 v9, 0, v216, s[38:39]
	v_add_u32_e32 v7, v9, v7
	v_and_b32_e32 v9, 0x7fffff, v6
	v_or_b32_e32 v9, 0x800000, v9
	v_mad_u64_u32 v[10:11], s[28:29], v9, s4, 0
	v_mov_b32_e32 v12, v11
	s_mov_b32 s4, 0x3c439041
	v_mad_u64_u32 v[12:13], s[28:29], v9, s4, v[12:13]
	v_mov_b32_e32 v14, v13
	s_mov_b32 s4, 0xdb629599
	v_mad_u64_u32 v[14:15], s[28:29], v9, s4, v[14:15]
	v_mov_b32_e32 v16, v15
	s_mov_b32 s4, 0xf534ddc0
	v_mad_u64_u32 v[16:17], s[28:29], v9, s4, v[16:17]
	v_mov_b32_e32 v18, v17
	s_mov_b32 s4, 0xfc2757d1
	v_mad_u64_u32 v[18:19], s[28:29], v9, s4, v[18:19]
	v_mov_b32_e32 v20, v19
	s_mov_b32 s4, 0x4e441529
	v_mad_u64_u32 v[20:21], s[28:29], v9, s4, v[20:21]
	v_mov_b32_e32 v22, v21
	v_mov_b32_e32 v23, v131
	s_mov_b32 s4, 0xa2f9836e
	v_mad_u64_u32 v[22:23], s[28:29], v9, s4, v[22:23]
	v_cndmask_b32_e32 v11, v20, v16, vcc
	v_cndmask_b32_e32 v9, v22, v18, vcc
	v_cndmask_b32_e32 v15, v23, v20, vcc
	v_cndmask_b32_e64 v13, v9, v11, s[36:37]
	v_cndmask_b32_e64 v9, v15, v9, s[36:37]
	v_cndmask_b32_e32 v15, v18, v14, vcc
	v_cndmask_b32_e64 v11, v11, v15, s[36:37]
	v_cndmask_b32_e64 v9, v9, v13, s[38:39]
	v_cndmask_b32_e64 v13, v13, v11, s[38:39]
	v_sub_u32_e32 v17, 32, v7
	v_alignbit_b32 v18, v9, v13, v17
	v_cmp_eq_u32_e64 s[40:41], 0, v7
	v_cndmask_b32_e32 v10, v14, v10, vcc
	s_mov_b32 s4, 0x3fc90fda
	v_cndmask_b32_e64 v7, v18, v9, s[40:41]
	v_cndmask_b32_e32 v9, v16, v12, vcc
	v_cndmask_b32_e64 v12, v15, v9, s[36:37]
	v_cndmask_b32_e64 v11, v11, v12, s[38:39]
	v_alignbit_b32 v15, v13, v11, v17
	v_cndmask_b32_e64 v13, v15, v13, s[40:41]
	v_bfe_u32 v18, v7, 29, 1
	v_cndmask_b32_e64 v9, v9, v10, s[36:37]
	v_alignbit_b32 v15, v7, v13, 30
	v_sub_u32_e32 v19, 0, v18
	v_cndmask_b32_e64 v9, v12, v9, s[38:39]
	v_xor_b32_e32 v15, v15, v19
	v_alignbit_b32 v10, v11, v9, v17
	v_cndmask_b32_e64 v10, v10, v11, s[40:41]
	v_ffbh_u32_e32 v12, v15
	v_alignbit_b32 v11, v13, v10, 30
	v_min_u32_e32 v12, 32, v12
	v_alignbit_b32 v9, v10, v9, 30
	v_xor_b32_e32 v11, v11, v19
	v_sub_u32_e32 v13, 31, v12
	v_xor_b32_e32 v9, v9, v19
	v_alignbit_b32 v14, v15, v11, v13
	v_alignbit_b32 v9, v11, v9, v13
	v_alignbit_b32 v10, v14, v9, 9
	v_ffbh_u32_e32 v11, v10
	v_min_u32_e32 v11, 32, v11
	v_lshrrev_b32_e32 v16, 29, v7
	v_not_b32_e32 v13, v11
	v_alignbit_b32 v9, v10, v9, v13
	v_lshlrev_b32_e32 v10, 31, v16
	v_or_b32_e32 v13, 0x33000000, v10
	v_add_lshl_u32 v11, v11, v12, 23
	v_lshrrev_b32_e32 v9, 9, v9
	v_sub_u32_e32 v11, v13, v11
	v_or_b32_e32 v10, 0.5, v10
	v_lshlrev_b32_e32 v12, 23, v12
	v_or_b32_e32 v9, v11, v9
	v_lshrrev_b32_e32 v11, 9, v14
	v_sub_u32_e32 v10, v10, v12
	v_or_b32_e32 v10, v11, v10
	v_mul_f32_e32 v11, 0x3fc90fda, v10
	v_fma_f32 v12, v10, s4, -v11
	v_fmac_f32_e32 v12, 0x33a22168, v10
	v_fmac_f32_e32 v12, 0x3fc90fda, v9
	v_lshrrev_b32_e32 v7, 30, v7
	v_add_f32_e32 v9, v11, v12
	v_add_u32_e32 v7, v18, v7

.LBB0_468:
	v_lshl_add_u64 v[196:197], v[2:3], 0, s[26:27]
	global_load_dword v132, v[196:197], off
	global_load_dword v133, v[196:197], off offset:256
	global_load_dword v134, v[196:197], off offset:512
	global_load_dword v135, v[196:197], off offset:768
	global_load_dword v136, v[196:197], off offset:1024
	global_load_dword v137, v[196:197], off offset:1280
	global_load_dword v138, v[196:197], off offset:1536
	global_load_dword v139, v[196:197], off offset:1792
	global_load_dword v140, v[196:197], off offset:2048
	global_load_dword v141, v[196:197], off offset:2304
	global_load_dword v142, v[196:197], off offset:2560
	global_load_dword v143, v[196:197], off offset:2816
	global_load_dword v144, v[196:197], off offset:3072
	global_load_dword v145, v[196:197], off offset:3328
	global_load_dword v146, v[196:197], off offset:3584
	global_load_dword v147, v[196:197], off offset:3840
	s_add_u32 s26, s26, 0x1000
	s_addc_u32 s27, s27, 0
	v_lshl_add_u64 v[196:197], v[2:3], 0, s[26:27]
	global_load_dword v148, v[196:197], off
	global_load_dword v149, v[196:197], off offset:256
	global_load_dword v150, v[196:197], off offset:512
	global_load_dword v151, v[196:197], off offset:768
	global_load_dword v152, v[196:197], off offset:1024
	global_load_dword v153, v[196:197], off offset:1280
	global_load_dword v154, v[196:197], off offset:1536
	global_load_dword v155, v[196:197], off offset:1792
	global_load_dword v156, v[196:197], off offset:2048
	global_load_dword v157, v[196:197], off offset:2304
	global_load_dword v158, v[196:197], off offset:2560
	global_load_dword v159, v[196:197], off offset:2816
	global_load_dword v160, v[196:197], off offset:3072
	global_load_dword v161, v[196:197], off offset:3328
	global_load_dword v162, v[196:197], off offset:3584
	global_load_dword v163, v[196:197], off offset:3840
	s_add_u32 s26, s26, 0x1000
	s_addc_u32 s27, s27, 0
	v_lshl_add_u64 v[196:197], v[2:3], 0, s[26:27]
	global_load_dword v164, v[196:197], off
	global_load_dword v165, v[196:197], off offset:256
	global_load_dword v166, v[196:197], off offset:512
	global_load_dword v167, v[196:197], off offset:768
	global_load_dword v168, v[196:197], off offset:1024
	global_load_dword v169, v[196:197], off offset:1280
	global_load_dword v170, v[196:197], off offset:1536
	global_load_dword v171, v[196:197], off offset:1792
	global_load_dword v172, v[196:197], off offset:2048
	global_load_dword v173, v[196:197], off offset:2304
	global_load_dword v174, v[196:197], off offset:2560
	global_load_dword v175, v[196:197], off offset:2816
	global_load_dword v176, v[196:197], off offset:3072
	global_load_dword v177, v[196:197], off offset:3328
	global_load_dword v178, v[196:197], off offset:3584
	global_load_dword v179, v[196:197], off offset:3840
	s_add_u32 s26, s26, 0x1000
	s_addc_u32 s27, s27, 0
	v_lshl_add_u64 v[196:197], v[2:3], 0, s[26:27]
	global_load_dword v180, v[196:197], off
	global_load_dword v181, v[196:197], off offset:256
	global_load_dword v182, v[196:197], off offset:512
	global_load_dword v183, v[196:197], off offset:768
	global_load_dword v184, v[196:197], off offset:1024
	global_load_dword v185, v[196:197], off offset:1280
	global_load_dword v186, v[196:197], off offset:1536
	global_load_dword v187, v[196:197], off offset:1792
	global_load_dword v188, v[196:197], off offset:2048
	global_load_dword v189, v[196:197], off offset:2304
	global_load_dword v190, v[196:197], off offset:2560
	global_load_dword v191, v[196:197], off offset:2816
	global_load_dword v192, v[196:197], off offset:3072
	global_load_dword v193, v[196:197], off offset:3328
	global_load_dword v194, v[196:197], off offset:3584
	global_load_dword v195, v[196:197], off offset:3840
	s_add_u32 s26, s26, 0x1000
	s_addc_u32 s27, s27, 0
	s_cmpk_eq_i32 s26, 0x4000
	ds_read_b128 v[10:13], v7
	ds_read_b128 v[14:17], v7 offset:16
	ds_read_b128 v[18:21], v7 offset:32
	ds_read_b128 v[22:25], v7 offset:48
	v_add_u32_e32 v7, 64, v7
	s_waitcnt vmcnt(63) lgkmcnt(3)
	v_fmac_f32_e32 v9, v10, v132
	s_waitcnt vmcnt(62)
	v_fmac_f32_e32 v9, v11, v133
	s_waitcnt vmcnt(61)
	v_fmac_f32_e32 v9, v12, v134
	s_waitcnt vmcnt(60)
	v_fmac_f32_e32 v9, v13, v135
	s_waitcnt vmcnt(59) lgkmcnt(2)
	v_fmac_f32_e32 v9, v14, v136
	s_waitcnt vmcnt(58)
	v_fmac_f32_e32 v9, v15, v137
	s_waitcnt vmcnt(57)
	v_fmac_f32_e32 v9, v16, v138
	s_waitcnt vmcnt(56)
	v_fmac_f32_e32 v9, v17, v139
	s_waitcnt vmcnt(55) lgkmcnt(1)
	v_fmac_f32_e32 v9, v18, v140
	s_waitcnt vmcnt(54)
	v_fmac_f32_e32 v9, v19, v141
	s_waitcnt vmcnt(53)
	v_fmac_f32_e32 v9, v20, v142
	s_waitcnt vmcnt(52)
	v_fmac_f32_e32 v9, v21, v143
	s_waitcnt vmcnt(51) lgkmcnt(0)
	v_fmac_f32_e32 v9, v22, v144
	s_waitcnt vmcnt(50)
	v_fmac_f32_e32 v9, v23, v145
	s_waitcnt vmcnt(49)
	v_fmac_f32_e32 v9, v24, v146
	s_waitcnt vmcnt(48)
	v_fmac_f32_e32 v9, v25, v147
	ds_read_b128 v[10:13], v7
	ds_read_b128 v[14:17], v7 offset:16
	ds_read_b128 v[18:21], v7 offset:32
	ds_read_b128 v[22:25], v7 offset:48
	v_add_u32_e32 v7, 64, v7
	s_waitcnt vmcnt(47) lgkmcnt(3)
	v_fmac_f32_e32 v9, v10, v148
	s_waitcnt vmcnt(46)
	v_fmac_f32_e32 v9, v11, v149
	s_waitcnt vmcnt(45)
	v_fmac_f32_e32 v9, v12, v150
	s_waitcnt vmcnt(44)
	v_fmac_f32_e32 v9, v13, v151
	s_waitcnt vmcnt(43) lgkmcnt(2)
	v_fmac_f32_e32 v9, v14, v152
	s_waitcnt vmcnt(42)
	v_fmac_f32_e32 v9, v15, v153
	s_waitcnt vmcnt(41)
	v_fmac_f32_e32 v9, v16, v154
	s_waitcnt vmcnt(40)
	v_fmac_f32_e32 v9, v17, v155
	s_waitcnt vmcnt(39) lgkmcnt(1)
	v_fmac_f32_e32 v9, v18, v156
	s_waitcnt vmcnt(38)
	v_fmac_f32_e32 v9, v19, v157
	s_waitcnt vmcnt(37)
	v_fmac_f32_e32 v9, v20, v158
	s_waitcnt vmcnt(36)
	v_fmac_f32_e32 v9, v21, v159
	s_waitcnt vmcnt(35) lgkmcnt(0)
	v_fmac_f32_e32 v9, v22, v160
	s_waitcnt vmcnt(34)
	v_fmac_f32_e32 v9, v23, v161
	s_waitcnt vmcnt(33)
	v_fmac_f32_e32 v9, v24, v162
	s_waitcnt vmcnt(32)
	v_fmac_f32_e32 v9, v25, v163
	ds_read_b128 v[10:13], v7
	ds_read_b128 v[14:17], v7 offset:16
	ds_read_b128 v[18:21], v7 offset:32
	ds_read_b128 v[22:25], v7 offset:48
	v_add_u32_e32 v7, 64, v7
	s_waitcnt vmcnt(31) lgkmcnt(3)
	v_fmac_f32_e32 v9, v10, v164
	s_waitcnt vmcnt(30)
	v_fmac_f32_e32 v9, v11, v165
	s_waitcnt vmcnt(29)
	v_fmac_f32_e32 v9, v12, v166
	s_waitcnt vmcnt(28)
	v_fmac_f32_e32 v9, v13, v167
	s_waitcnt vmcnt(27) lgkmcnt(2)
	v_fmac_f32_e32 v9, v14, v168
	s_waitcnt vmcnt(26)
	v_fmac_f32_e32 v9, v15, v169
	s_waitcnt vmcnt(25)
	v_fmac_f32_e32 v9, v16, v170
	s_waitcnt vmcnt(24)
	v_fmac_f32_e32 v9, v17, v171
	s_waitcnt vmcnt(23) lgkmcnt(1)
	v_fmac_f32_e32 v9, v18, v172
	s_waitcnt vmcnt(22)
	v_fmac_f32_e32 v9, v19, v173
	s_waitcnt vmcnt(21)
	v_fmac_f32_e32 v9, v20, v174
	s_waitcnt vmcnt(20)
	v_fmac_f32_e32 v9, v21, v175
	s_waitcnt vmcnt(19) lgkmcnt(0)
	v_fmac_f32_e32 v9, v22, v176
	s_waitcnt vmcnt(18)
	v_fmac_f32_e32 v9, v23, v177
	s_waitcnt vmcnt(17)
	v_fmac_f32_e32 v9, v24, v178
	s_waitcnt vmcnt(16)
	v_fmac_f32_e32 v9, v25, v179
	ds_read_b128 v[10:13], v7
	ds_read_b128 v[14:17], v7 offset:16
	ds_read_b128 v[18:21], v7 offset:32
	ds_read_b128 v[22:25], v7 offset:48
	v_add_u32_e32 v7, 64, v7
	s_waitcnt vmcnt(15) lgkmcnt(3)
	v_fmac_f32_e32 v9, v10, v180
	s_waitcnt vmcnt(14)
	v_fmac_f32_e32 v9, v11, v181
	s_waitcnt vmcnt(13)
	v_fmac_f32_e32 v9, v12, v182
	s_waitcnt vmcnt(12)
	v_fmac_f32_e32 v9, v13, v183
	s_waitcnt vmcnt(11) lgkmcnt(2)
	v_fmac_f32_e32 v9, v14, v184
	s_waitcnt vmcnt(10)
	v_fmac_f32_e32 v9, v15, v185
	s_waitcnt vmcnt(9)
	v_fmac_f32_e32 v9, v16, v186
	s_waitcnt vmcnt(8)
	v_fmac_f32_e32 v9, v17, v187
	s_waitcnt vmcnt(7) lgkmcnt(1)
	v_fmac_f32_e32 v9, v18, v188
	s_waitcnt vmcnt(6)
	v_fmac_f32_e32 v9, v19, v189
	s_waitcnt vmcnt(5)
	v_fmac_f32_e32 v9, v20, v190
	s_waitcnt vmcnt(4)
	v_fmac_f32_e32 v9, v21, v191
	s_waitcnt vmcnt(3) lgkmcnt(0)
	v_fmac_f32_e32 v9, v22, v192
	s_waitcnt vmcnt(2)
	v_fmac_f32_e32 v9, v23, v193
	s_waitcnt vmcnt(1)
	v_fmac_f32_e32 v9, v24, v194
	s_waitcnt vmcnt(0)
	v_fmac_f32_e32 v9, v25, v195
	global_load_dword v4, v[4:5], off
	s_brev_b32 s4, 18
	s_waitcnt vmcnt(0)
	v_mul_f32_e32 v5, v9, v4
	v_and_b32_e32 v7, 0x7fffffff, v5
	v_cmp_nlt_f32_e64 s[26:27], |v5|, s4
	s_and_saveexec_b64 s[28:29], s[26:27]
	s_xor_b64 s[26:27], exec, s[28:29]
	s_cbranch_execz .LBB0_471
	v_lshrrev_b32_e32 v9, 23, v7
	v_add_u32_e32 v9, 0xffffff88, v9
	v_cmp_lt_u32_e32 vcc, 63, v9
	s_mov_b32 s4, 0xfe5163ab
	s_nop 0
	v_cndmask_b32_e32 v10, 0, v215, vcc
	v_add_u32_e32 v9, v10, v9
	v_cmp_lt_u32_e64 s[36:37], 31, v9
	s_nop 1
	v_cndmask_b32_e64 v10, 0, v216, s[36:37]
	v_add_u32_e32 v9, v10, v9
	v_cmp_lt_u32_e64 s[38:39], 31, v9
	s_nop 1
	v_cndmask_b32_e64 v10, 0, v216, s[38:39]
	v_add_u32_e32 v9, v10, v9
	v_and_b32_e32 v10, 0x7fffff, v7
	v_or_b32_e32 v22, 0x800000, v10
	v_mad_u64_u32 v[10:11], s[28:29], v22, s4, 0
	v_mov_b32_e32 v130, v11
	s_mov_b32 s4, 0x3c439041
	v_mad_u64_u32 v[12:13], s[28:29], v22, s4, v[130:131]
	v_mov_b32_e32 v130, v13
	s_mov_b32 s4, 0xdb629599
	v_mad_u64_u32 v[14:15], s[28:29], v22, s4, v[130:131]
	v_mov_b32_e32 v130, v15
	s_mov_b32 s4, 0xf534ddc0
	v_mad_u64_u32 v[16:17], s[28:29], v22, s4, v[130:131]
	v_mov_b32_e32 v130, v17
	s_mov_b32 s4, 0xfc2757d1
	v_mad_u64_u32 v[18:19], s[28:29], v22, s4, v[130:131]
	v_mov_b32_e32 v130, v19
	s_mov_b32 s4, 0x4e441529
	v_mad_u64_u32 v[20:21], s[28:29], v22, s4, v[130:131]
	v_mov_b32_e32 v130, v21
	s_mov_b32 s4, 0xa2f9836e
	v_mad_u64_u32 v[22:23], s[28:29], v22, s4, v[130:131]
	v_cndmask_b32_e32 v11, v20, v16, vcc
	v_cndmask_b32_e32 v13, v22, v18, vcc
	v_cndmask_b32_e32 v17, v23, v20, vcc
	v_cndmask_b32_e64 v15, v13, v11, s[36:37]
	v_cndmask_b32_e64 v13, v17, v13, s[36:37]
	v_cndmask_b32_e32 v17, v18, v14, vcc
	v_cndmask_b32_e64 v11, v11, v17, s[36:37]
	v_cndmask_b32_e64 v13, v13, v15, s[38:39]
	v_cndmask_b32_e64 v15, v15, v11, s[38:39]
	v_sub_u32_e32 v18, 32, v9
	v_alignbit_b32 v19, v13, v15, v18
	v_cmp_eq_u32_e64 s[40:41], 0, v9
	v_cndmask_b32_e32 v12, v16, v12, vcc
	v_cndmask_b32_e32 v10, v14, v10, vcc
	v_cndmask_b32_e64 v9, v19, v13, s[40:41]
	v_cndmask_b32_e64 v13, v17, v12, s[36:37]
	v_cndmask_b32_e64 v11, v11, v13, s[38:39]
	v_alignbit_b32 v16, v15, v11, v18
	v_cndmask_b32_e64 v15, v16, v15, s[40:41]
	v_bfe_u32 v19, v9, 29, 1
	v_cndmask_b32_e64 v10, v12, v10, s[36:37]
	v_alignbit_b32 v16, v9, v15, 30
	v_sub_u32_e32 v20, 0, v19
	v_cndmask_b32_e64 v10, v13, v10, s[38:39]
	v_xor_b32_e32 v16, v16, v20
	v_alignbit_b32 v12, v11, v10, v18
	v_cndmask_b32_e64 v11, v12, v11, s[40:41]
	v_ffbh_u32_e32 v13, v16
	v_alignbit_b32 v12, v15, v11, 30
	v_min_u32_e32 v13, 32, v13
	v_alignbit_b32 v10, v11, v10, 30
	v_xor_b32_e32 v12, v12, v20
	v_sub_u32_e32 v14, 31, v13
	v_xor_b32_e32 v10, v10, v20
	v_alignbit_b32 v15, v16, v12, v14
	v_alignbit_b32 v10, v12, v10, v14
	v_alignbit_b32 v11, v15, v10, 9
	v_ffbh_u32_e32 v12, v11
	v_min_u32_e32 v12, 32, v12
	v_lshrrev_b32_e32 v17, 29, v9
	v_not_b32_e32 v14, v12
	v_alignbit_b32 v10, v11, v10, v14
	v_lshlrev_b32_e32 v11, 31, v17
	v_or_b32_e32 v14, 0x33000000, v11
	v_add_lshl_u32 v12, v12, v13, 23
	v_lshrrev_b32_e32 v10, 9, v10
	v_sub_u32_e32 v12, v14, v12
	v_or_b32_e32 v11, 0.5, v11
	v_lshlrev_b32_e32 v13, 23, v13
	v_or_b32_e32 v10, v12, v10
	v_lshrrev_b32_e32 v12, 9, v15
	v_sub_u32_e32 v11, v11, v13
	v_or_b32_e32 v11, v12, v11
	v_mul_f32_e32 v12, 0x3fc90fda, v11
	s_mov_b32 s4, 0x3fc90fda
	v_fma_f32 v13, v11, s4, -v12
	v_fmac_f32_e32 v13, 0x33a22168, v11
	v_fmac_f32_e32 v13, 0x3fc90fda, v10
	v_lshrrev_b32_e32 v9, 30, v9
	v_add_f32_e32 v10, v12, v13
	v_add_u32_e32 v9, v19, v9

.LBB0_474:
	v_lshl_add_u64 v[196:197], v[2:3], 0, s[26:27]
	global_load_dword v132, v[196:197], off
	global_load_dword v133, v[196:197], off offset:256
	global_load_dword v134, v[196:197], off offset:512
	global_load_dword v135, v[196:197], off offset:768
	global_load_dword v136, v[196:197], off offset:1024
	global_load_dword v137, v[196:197], off offset:1280
	global_load_dword v138, v[196:197], off offset:1536
	global_load_dword v139, v[196:197], off offset:1792
	global_load_dword v140, v[196:197], off offset:2048
	global_load_dword v141, v[196:197], off offset:2304
	global_load_dword v142, v[196:197], off offset:2560
	global_load_dword v143, v[196:197], off offset:2816
	global_load_dword v144, v[196:197], off offset:3072
	global_load_dword v145, v[196:197], off offset:3328
	global_load_dword v146, v[196:197], off offset:3584
	global_load_dword v147, v[196:197], off offset:3840
	s_add_u32 s26, s26, 0x1000
	s_addc_u32 s27, s27, 0
	v_lshl_add_u64 v[196:197], v[2:3], 0, s[26:27]
	global_load_dword v148, v[196:197], off
	global_load_dword v149, v[196:197], off offset:256
	global_load_dword v150, v[196:197], off offset:512
	global_load_dword v151, v[196:197], off offset:768
	global_load_dword v152, v[196:197], off offset:1024
	global_load_dword v153, v[196:197], off offset:1280
	global_load_dword v154, v[196:197], off offset:1536
	global_load_dword v155, v[196:197], off offset:1792
	global_load_dword v156, v[196:197], off offset:2048
	global_load_dword v157, v[196:197], off offset:2304
	global_load_dword v158, v[196:197], off offset:2560
	global_load_dword v159, v[196:197], off offset:2816
	global_load_dword v160, v[196:197], off offset:3072
	global_load_dword v161, v[196:197], off offset:3328
	global_load_dword v162, v[196:197], off offset:3584
	global_load_dword v163, v[196:197], off offset:3840
	s_add_u32 s26, s26, 0x1000
	s_addc_u32 s27, s27, 0
	v_lshl_add_u64 v[196:197], v[2:3], 0, s[26:27]
	global_load_dword v164, v[196:197], off
	global_load_dword v165, v[196:197], off offset:256
	global_load_dword v166, v[196:197], off offset:512
	global_load_dword v167, v[196:197], off offset:768
	global_load_dword v168, v[196:197], off offset:1024
	global_load_dword v169, v[196:197], off offset:1280
	global_load_dword v170, v[196:197], off offset:1536
	global_load_dword v171, v[196:197], off offset:1792
	global_load_dword v172, v[196:197], off offset:2048
	global_load_dword v173, v[196:197], off offset:2304
	global_load_dword v174, v[196:197], off offset:2560
	global_load_dword v175, v[196:197], off offset:2816
	global_load_dword v176, v[196:197], off offset:3072
	global_load_dword v177, v[196:197], off offset:3328
	global_load_dword v178, v[196:197], off offset:3584
	global_load_dword v179, v[196:197], off offset:3840
	s_add_u32 s26, s26, 0x1000
	s_addc_u32 s27, s27, 0
	v_lshl_add_u64 v[196:197], v[2:3], 0, s[26:27]
	global_load_dword v180, v[196:197], off
	global_load_dword v181, v[196:197], off offset:256
	global_load_dword v182, v[196:197], off offset:512
	global_load_dword v183, v[196:197], off offset:768
	global_load_dword v184, v[196:197], off offset:1024
	global_load_dword v185, v[196:197], off offset:1280
	global_load_dword v186, v[196:197], off offset:1536
	global_load_dword v187, v[196:197], off offset:1792
	global_load_dword v188, v[196:197], off offset:2048
	global_load_dword v189, v[196:197], off offset:2304
	global_load_dword v190, v[196:197], off offset:2560
	global_load_dword v191, v[196:197], off offset:2816
	global_load_dword v192, v[196:197], off offset:3072
	global_load_dword v193, v[196:197], off offset:3328
	global_load_dword v194, v[196:197], off offset:3584
	global_load_dword v195, v[196:197], off offset:3840
	s_add_u32 s26, s26, 0x1000
	s_addc_u32 s27, s27, 0
	s_cmpk_lg_i32 s26, 0x4000
	ds_read_b128 v[8:11], v5
	ds_read_b128 v[12:15], v5 offset:16
	ds_read_b128 v[16:19], v5 offset:32
	ds_read_b128 v[20:23], v5 offset:48
	v_add_u32_e32 v5, 64, v5
	s_waitcnt vmcnt(63) lgkmcnt(3)
	v_fmac_f32_e32 v6, v8, v132
	s_waitcnt vmcnt(62)
	v_fmac_f32_e32 v6, v9, v133
	s_waitcnt vmcnt(61)
	v_fmac_f32_e32 v6, v10, v134
	s_waitcnt vmcnt(60)
	v_fmac_f32_e32 v6, v11, v135
	s_waitcnt vmcnt(59) lgkmcnt(2)
	v_fmac_f32_e32 v6, v12, v136
	s_waitcnt vmcnt(58)
	v_fmac_f32_e32 v6, v13, v137
	s_waitcnt vmcnt(57)
	v_fmac_f32_e32 v6, v14, v138
	s_waitcnt vmcnt(56)
	v_fmac_f32_e32 v6, v15, v139
	s_waitcnt vmcnt(55) lgkmcnt(1)
	v_fmac_f32_e32 v6, v16, v140
	s_waitcnt vmcnt(54)
	v_fmac_f32_e32 v6, v17, v141
	s_waitcnt vmcnt(53)
	v_fmac_f32_e32 v6, v18, v142
	s_waitcnt vmcnt(52)
	v_fmac_f32_e32 v6, v19, v143
	s_waitcnt vmcnt(51) lgkmcnt(0)
	v_fmac_f32_e32 v6, v20, v144
	s_waitcnt vmcnt(50)
	v_fmac_f32_e32 v6, v21, v145
	s_waitcnt vmcnt(49)
	v_fmac_f32_e32 v6, v22, v146
	s_waitcnt vmcnt(48)
	v_fmac_f32_e32 v6, v23, v147
	ds_read_b128 v[8:11], v5
	ds_read_b128 v[12:15], v5 offset:16
	ds_read_b128 v[16:19], v5 offset:32
	ds_read_b128 v[20:23], v5 offset:48
	v_add_u32_e32 v5, 64, v5
	s_waitcnt vmcnt(47) lgkmcnt(3)
	v_fmac_f32_e32 v6, v8, v148
	s_waitcnt vmcnt(46)
	v_fmac_f32_e32 v6, v9, v149
	s_waitcnt vmcnt(45)
	v_fmac_f32_e32 v6, v10, v150
	s_waitcnt vmcnt(44)
	v_fmac_f32_e32 v6, v11, v151
	s_waitcnt vmcnt(43) lgkmcnt(2)
	v_fmac_f32_e32 v6, v12, v152
	s_waitcnt vmcnt(42)
	v_fmac_f32_e32 v6, v13, v153
	s_waitcnt vmcnt(41)
	v_fmac_f32_e32 v6, v14, v154
	s_waitcnt vmcnt(40)
	v_fmac_f32_e32 v6, v15, v155
	s_waitcnt vmcnt(39) lgkmcnt(1)
	v_fmac_f32_e32 v6, v16, v156
	s_waitcnt vmcnt(38)
	v_fmac_f32_e32 v6, v17, v157
	s_waitcnt vmcnt(37)
	v_fmac_f32_e32 v6, v18, v158
	s_waitcnt vmcnt(36)
	v_fmac_f32_e32 v6, v19, v159
	s_waitcnt vmcnt(35) lgkmcnt(0)
	v_fmac_f32_e32 v6, v20, v160
	s_waitcnt vmcnt(34)
	v_fmac_f32_e32 v6, v21, v161
	s_waitcnt vmcnt(33)
	v_fmac_f32_e32 v6, v22, v162
	s_waitcnt vmcnt(32)
	v_fmac_f32_e32 v6, v23, v163
	ds_read_b128 v[8:11], v5
	ds_read_b128 v[12:15], v5 offset:16
	ds_read_b128 v[16:19], v5 offset:32
	ds_read_b128 v[20:23], v5 offset:48
	v_add_u32_e32 v5, 64, v5
	s_waitcnt vmcnt(31) lgkmcnt(3)
	v_fmac_f32_e32 v6, v8, v164
	s_waitcnt vmcnt(30)
	v_fmac_f32_e32 v6, v9, v165
	s_waitcnt vmcnt(29)
	v_fmac_f32_e32 v6, v10, v166
	s_waitcnt vmcnt(28)
	v_fmac_f32_e32 v6, v11, v167
	s_waitcnt vmcnt(27) lgkmcnt(2)
	v_fmac_f32_e32 v6, v12, v168
	s_waitcnt vmcnt(26)
	v_fmac_f32_e32 v6, v13, v169
	s_waitcnt vmcnt(25)
	v_fmac_f32_e32 v6, v14, v170
	s_waitcnt vmcnt(24)
	v_fmac_f32_e32 v6, v15, v171
	s_waitcnt vmcnt(23) lgkmcnt(1)
	v_fmac_f32_e32 v6, v16, v172
	s_waitcnt vmcnt(22)
	v_fmac_f32_e32 v6, v17, v173
	s_waitcnt vmcnt(21)
	v_fmac_f32_e32 v6, v18, v174
	s_waitcnt vmcnt(20)
	v_fmac_f32_e32 v6, v19, v175
	s_waitcnt vmcnt(19) lgkmcnt(0)
	v_fmac_f32_e32 v6, v20, v176
	s_waitcnt vmcnt(18)
	v_fmac_f32_e32 v6, v21, v177
	s_waitcnt vmcnt(17)
	v_fmac_f32_e32 v6, v22, v178
	s_waitcnt vmcnt(16)
	v_fmac_f32_e32 v6, v23, v179
	ds_read_b128 v[8:11], v5
	ds_read_b128 v[12:15], v5 offset:16
	ds_read_b128 v[16:19], v5 offset:32
	ds_read_b128 v[20:23], v5 offset:48
	v_add_u32_e32 v5, 64, v5
	s_waitcnt vmcnt(15) lgkmcnt(3)
	v_fmac_f32_e32 v6, v8, v180
	s_waitcnt vmcnt(14)
	v_fmac_f32_e32 v6, v9, v181
	s_waitcnt vmcnt(13)
	v_fmac_f32_e32 v6, v10, v182
	s_waitcnt vmcnt(12)
	v_fmac_f32_e32 v6, v11, v183
	s_waitcnt vmcnt(11) lgkmcnt(2)
	v_fmac_f32_e32 v6, v12, v184
	s_waitcnt vmcnt(10)
	v_fmac_f32_e32 v6, v13, v185
	s_waitcnt vmcnt(9)
	v_fmac_f32_e32 v6, v14, v186
	s_waitcnt vmcnt(8)
	v_fmac_f32_e32 v6, v15, v187
	s_waitcnt vmcnt(7) lgkmcnt(1)
	v_fmac_f32_e32 v6, v16, v188
	s_waitcnt vmcnt(6)
	v_fmac_f32_e32 v6, v17, v189
	s_waitcnt vmcnt(5)
	v_fmac_f32_e32 v6, v18, v190
	s_waitcnt vmcnt(4)
	v_fmac_f32_e32 v6, v19, v191
	s_waitcnt vmcnt(3) lgkmcnt(0)
	v_fmac_f32_e32 v6, v20, v192
	s_waitcnt vmcnt(2)
	v_fmac_f32_e32 v6, v21, v193
	s_waitcnt vmcnt(1)
	v_fmac_f32_e32 v6, v22, v194
	s_waitcnt vmcnt(0)
	v_fmac_f32_e32 v6, v23, v195
	v_mul_f32_e32 v2, v4, v6
	s_brev_b32 s4, 18
	v_and_b32_e32 v3, 0x7fffffff, v2
	v_cmp_nlt_f32_e64 s[26:27], |v2|, s4
	s_and_saveexec_b64 s[28:29], s[26:27]
	s_xor_b64 s[26:27], exec, s[28:29]
	s_cbranch_execz .LBB0_477
	v_lshrrev_b32_e32 v4, 23, v3
	v_add_u32_e32 v4, 0xffffff88, v4
	v_cmp_lt_u32_e32 vcc, 63, v4
	s_mov_b32 s4, 0xfe5163ab
	s_nop 0
	v_cndmask_b32_e32 v5, 0, v215, vcc
	v_add_u32_e32 v4, v5, v4
	v_cmp_lt_u32_e64 s[36:37], 31, v4
	s_nop 1
	v_cndmask_b32_e64 v5, 0, v216, s[36:37]
	v_add_u32_e32 v4, v5, v4
	v_cmp_lt_u32_e64 s[38:39], 31, v4
	s_nop 1
	v_cndmask_b32_e64 v5, 0, v216, s[38:39]
	v_add_u32_e32 v18, v5, v4
	v_and_b32_e32 v4, 0x7fffff, v3
	v_or_b32_e32 v16, 0x800000, v4
	v_mad_u64_u32 v[4:5], s[28:29], v16, s4, 0
	v_mov_b32_e32 v130, v5
	s_mov_b32 s4, 0x3c439041
	v_mad_u64_u32 v[6:7], s[28:29], v16, s4, v[130:131]
	v_mov_b32_e32 v130, v7
	s_mov_b32 s4, 0xdb629599
	v_mad_u64_u32 v[8:9], s[28:29], v16, s4, v[130:131]
	v_mov_b32_e32 v130, v9
	s_mov_b32 s4, 0xf534ddc0
	v_mad_u64_u32 v[10:11], s[28:29], v16, s4, v[130:131]
	v_mov_b32_e32 v130, v11
	s_mov_b32 s4, 0xfc2757d1
	v_mad_u64_u32 v[12:13], s[28:29], v16, s4, v[130:131]
	v_mov_b32_e32 v130, v13
	s_mov_b32 s4, 0x4e441529
	v_mad_u64_u32 v[14:15], s[28:29], v16, s4, v[130:131]
	v_mov_b32_e32 v130, v15
	s_mov_b32 s4, 0xa2f9836e
	v_mad_u64_u32 v[16:17], s[28:29], v16, s4, v[130:131]
	v_cndmask_b32_e32 v5, v14, v10, vcc
	v_cndmask_b32_e32 v7, v16, v12, vcc
	v_cndmask_b32_e32 v11, v17, v14, vcc
	v_cndmask_b32_e64 v9, v7, v5, s[36:37]
	v_cndmask_b32_e64 v7, v11, v7, s[36:37]
	v_cndmask_b32_e32 v11, v12, v8, vcc
	v_cndmask_b32_e64 v5, v5, v11, s[36:37]
	v_cndmask_b32_e32 v6, v10, v6, vcc
	v_cndmask_b32_e64 v7, v7, v9, s[38:39]
	v_cndmask_b32_e64 v9, v9, v5, s[38:39]
	v_sub_u32_e32 v12, 32, v18
	v_cndmask_b32_e64 v10, v11, v6, s[36:37]
	v_alignbit_b32 v13, v7, v9, v12
	v_cmp_eq_u32_e64 s[40:41], 0, v18
	v_cndmask_b32_e64 v5, v5, v10, s[38:39]
	v_alignbit_b32 v11, v9, v5, v12
	v_cndmask_b32_e64 v7, v13, v7, s[40:41]
	v_cndmask_b32_e32 v4, v8, v4, vcc
	v_cndmask_b32_e64 v9, v11, v9, s[40:41]
	v_bfe_u32 v14, v7, 29, 1
	v_cndmask_b32_e64 v4, v6, v4, s[36:37]
	v_alignbit_b32 v11, v7, v9, 30
	v_sub_u32_e32 v15, 0, v14
	v_cndmask_b32_e64 v4, v10, v4, s[38:39]
	v_xor_b32_e32 v11, v11, v15
	v_alignbit_b32 v6, v5, v4, v12
	v_cndmask_b32_e64 v5, v6, v5, s[40:41]
	v_ffbh_u32_e32 v8, v11
	v_alignbit_b32 v6, v9, v5, 30
	v_min_u32_e32 v8, 32, v8
	v_alignbit_b32 v4, v5, v4, 30
	v_xor_b32_e32 v6, v6, v15
	v_sub_u32_e32 v9, 31, v8
	v_xor_b32_e32 v4, v4, v15
	v_alignbit_b32 v10, v11, v6, v9
	v_alignbit_b32 v4, v6, v4, v9
	v_alignbit_b32 v5, v10, v4, 9
	v_ffbh_u32_e32 v6, v5
	v_min_u32_e32 v6, 32, v6
	v_lshrrev_b32_e32 v13, 29, v7
	v_not_b32_e32 v9, v6
	v_alignbit_b32 v4, v5, v4, v9
	v_lshlrev_b32_e32 v5, 31, v13
	v_or_b32_e32 v9, 0x33000000, v5
	v_add_lshl_u32 v6, v6, v8, 23
	v_lshrrev_b32_e32 v4, 9, v4
	v_sub_u32_e32 v6, v9, v6
	v_or_b32_e32 v5, 0.5, v5
	v_lshlrev_b32_e32 v8, 23, v8
	v_or_b32_e32 v4, v6, v4
	v_lshrrev_b32_e32 v6, 9, v10
	v_sub_u32_e32 v5, v5, v8
	v_or_b32_e32 v5, v6, v5
	v_mul_f32_e32 v6, 0x3fc90fda, v5
	s_mov_b32 s4, 0x3fc90fda
	v_fma_f32 v8, v5, s4, -v6
	v_fmac_f32_e32 v8, 0x33a22168, v5
	v_fmac_f32_e32 v8, 0x3fc90fda, v4
	v_lshrrev_b32_e32 v4, 30, v7
	v_add_f32_e32 v5, v6, v8
	v_add_u32_e32 v4, v14, v4
